# P3 loop: last eight p1 row-sum adds and Q3 packs deferred into the next iteration's p0 QK shadow; p0 K fragments in V ring buffers
# baseline (speedup 1.0000x reference)
.LBB0_318:
	s_or_b32 s0, s78, 31
	s_or_b32 s1, s2, 64
	s_cmp_gt_u32 s1, s0
	s_cselect_b64 s[70:71], -1, 0
	s_cmp_lg_u64 s[70:71], 0
	s_subb_u32 s82, s33, 0
	s_sub_i32 s0, s72, s2
	v_cvt_f32_i32_e32 v38, s0
	v_lshrrev_b32_e32 v35, 2, v35
	v_lshlrev_b32_e32 v45, 1, v211
	v_and_b32_e32 v44, 12, v33
	v_fma_f32 v40, v208, v38, -v207
	v_fmamk_f32 v41, v208, 0x42000000, v40
	v_add_f32_e32 v16, v40, v16
	v_add_f32_e32 v0, v41, v0
	v_exp_f32_e32 v42, v16
	v_exp_f32_e32 v43, v0
	v_add_f32_e32 v0, v40, v17
	v_add_f32_e32 v1, v41, v1
	v_exp_f32_e32 v0, v0
	v_exp_f32_e32 v16, v1
	v_add_f32_e32 v17, v43, v42
	v_mov_b32_e32 v1, v113
	v_add_f32_e32 v2, v41, v2
	v_pk_add_f32 v[38:39], v[16:17], v[0:1]
	v_add_f32_e32 v1, v40, v18
	v_pk_add_f32 v[38:39], v[38:39], v[38:39] op_sel_hi:[0,1]
	v_exp_f32_e32 v17, v2
	v_add_f32_e32 v2, v40, v19
	v_exp_f32_e32 v1, v1
	v_exp_f32_e32 v38, v2
	v_add_f32_e32 v2, v41, v3
	v_exp_f32_e32 v2, v2
	v_add_f32_e32 v3, v17, v1
	v_add_f32_e32 v4, v41, v4
	v_add_f32_e32 v6, v41, v6
	v_pk_add_f32 v[18:19], v[2:3], v[38:39]
	v_add_f32_e32 v3, v40, v20
	v_pk_add_f32 v[18:19], v[18:19], v[18:19] op_sel_hi:[0,1]
	v_exp_f32_e32 v39, v4
	v_add_f32_e32 v4, v40, v21
	v_exp_f32_e32 v3, v3
	v_exp_f32_e32 v18, v4
	v_add_f32_e32 v4, v41, v5
	v_exp_f32_e32 v4, v4
	v_or_b32_e32 v5, v34, v35
	v_lshlrev_b32_e32 v35, 8, v5
	v_add_f32_e32 v5, v39, v3
	v_pk_add_f32 v[20:21], v[4:5], v[18:19]
	v_add_f32_e32 v5, v40, v22
	v_pk_add_f32 v[20:21], v[20:21], v[20:21] op_sel_hi:[0,1]
	v_exp_f32_e32 v19, v6
	v_add_f32_e32 v6, v40, v23
	v_exp_f32_e32 v5, v5
	v_exp_f32_e32 v20, v6
	v_add_f32_e32 v6, v41, v7
	v_exp_f32_e32 v6, v6
	v_add_f32_e32 v7, v19, v5
	v_add_f32_e32 v8, v41, v8
	v_add_f32_e32 v10, v41, v10
	v_pk_add_f32 v[22:23], v[6:7], v[20:21]
	v_add_f32_e32 v7, v40, v24
	v_pk_add_f32 v[22:23], v[22:23], v[22:23] op_sel_hi:[0,1]
	v_exp_f32_e32 v21, v8
	v_add_f32_e32 v8, v40, v25
	v_exp_f32_e32 v7, v7
	v_exp_f32_e32 v22, v8
	v_add_f32_e32 v8, v41, v9
	v_exp_f32_e32 v8, v8
	v_add_f32_e32 v9, v21, v7
	v_and_b32_e32 v45, 2, v45
	v_and_b32_e32 v37, 1, v37
	v_pk_add_f32 v[24:25], v[8:9], v[22:23]
	v_add_f32_e32 v9, v40, v26
	v_pk_add_f32 v[24:25], v[24:25], v[24:25] op_sel_hi:[0,1]
	v_exp_f32_e32 v23, v10
	v_add_f32_e32 v10, v40, v27
	v_exp_f32_e32 v9, v9
	v_exp_f32_e32 v24, v10
	v_add_f32_e32 v10, v41, v11
	v_exp_f32_e32 v10, v10
	v_or3_b32 v11, v44, v45, v37
	v_lshlrev_b32_e32 v37, 4, v11
	v_add_f32_e32 v11, v23, v9
	v_pk_add_f32 v[26:27], v[10:11], v[24:25]
	v_add_f32_e32 v12, v41, v12
	v_pk_add_f32 v[26:27], v[26:27], v[26:27] op_sel_hi:[0,1]
	v_add_f32_e32 v11, v40, v28
	v_exp_f32_e32 v25, v12
	v_add_f32_e32 v12, v40, v29
	v_exp_f32_e32 v11, v11
	v_exp_f32_e32 v26, v12
	v_add_f32_e32 v12, v41, v13
	v_exp_f32_e32 v12, v12
	v_lshlrev_b32_e32 v13, 3, v33
	v_and_b32_e32 v33, 8, v13
	v_add_f32_e32 v13, v25, v11
	v_pk_add_f32 v[28:29], v[12:13], v[26:27]
	v_add_f32_e32 v14, v41, v14
	v_pk_add_f32 v[28:29], v[28:29], v[28:29] op_sel_hi:[0,1]
	v_add_f32_e32 v13, v40, v30
	v_exp_f32_e32 v27, v14
	v_add_f32_e32 v14, v40, v31
	v_exp_f32_e32 v13, v13
	v_exp_f32_e32 v28, v14
	v_add_f32_e32 v14, v41, v15
	v_exp_f32_e32 v14, v14
	v_add_f32_e32 v15, v27, v13
	v_or3_b32 v235, v37, v35, v33
	s_mov_b32 s72, 0
	v_pk_add_f32 v[30:31], v[14:15], v[28:29]
	v_cvt_pk_bf16_f32 v152, v42, v0
	v_cvt_pk_bf16_f32 v153, v1, v38
	v_cvt_pk_bf16_f32 v154, v3, v18
	v_cvt_pk_bf16_f32 v155, v5, v20
	v_cvt_pk_bf16_f32 v156, v7, v22
	s_nop 0
	v_add_f32_e32 v15, v30, v31
	v_add_f32_e32 v229, 0, v15
	v_cvt_pk_bf16_f32 v157, v9, v24
	v_cvt_pk_bf16_f32 v158, v11, v26
	v_cvt_pk_bf16_f32 v159, v13, v28
	v_cvt_pk_bf16_f32 v148, v43, v16
	v_cvt_pk_bf16_f32 v149, v17, v2
	v_cvt_pk_bf16_f32 v150, v39, v4
	v_cvt_pk_bf16_f32 v151, v19, v6
	v_cvt_pk_bf16_f32 v160, v21, v8
	v_cvt_pk_bf16_f32 v161, v23, v10
	v_cvt_pk_bf16_f32 v162, v25, v12
	v_cvt_pk_bf16_f32 v163, v27, v14
	s_cmp_lt_i32 s82, 2
	v_xor_b32_e32 v236, 0x80, v235
	v_xor_b32_e32 v234, 0xc0, v235
	s_cbranch_scc1 .LBB0_331
	v_mov_b32_e32 v198, v21
	v_mov_b32_e32 v199, v8
	v_mov_b32_e32 v200, v23
	v_mov_b32_e32 v201, v10
	v_mov_b32_e32 v202, v25
	v_mov_b32_e32 v203, v12
	v_mov_b32_e32 v204, v27
	v_mov_b32_e32 v205, v14
	v_sub_f32_e32 v229, v229, v21
	v_sub_f32_e32 v229, v229, v8
	v_sub_f32_e32 v229, v229, v23
	v_sub_f32_e32 v229, v229, v10
	v_sub_f32_e32 v229, v229, v25
	v_sub_f32_e32 v229, v229, v12
	v_sub_f32_e32 v229, v229, v27
	v_sub_f32_e32 v229, v229, v14
	s_mov_b32 s97, s83
	s_lshl_b64 s[0:1], s[96:97], 13
	v_lshl_add_u64 v[0:1], v[212:213], 0, s[0:1]
	s_mov_b64 s[0:1], 0x106000
	v_lshl_add_u64 v[218:219], v[0:1], 0, s[0:1]
	s_mov_b64 s[0:1], 0x6000
	v_lshl_add_u64 v[220:221], v[0:1], 0, s[0:1]
	s_lshl_b64 s[0:1], s[96:97], 14
	v_lshl_add_u64 v[0:1], v[214:215], 0, s[0:1]
	s_mov_b64 s[4:5], 0xc000
	v_lshl_add_u64 v[222:223], v[0:1], 0, s[4:5]
	v_lshl_add_u64 v[0:1], v[216:217], 0, s[0:1]
	v_readlane_b32 s1, v244, 25
	s_add_i32 s1, s1, s2
	v_lshl_add_u64 v[224:225], v[0:1], 0, s[4:5]
	v_add_u32_e32 v0, s1, v32
	s_lshl_b32 s0, s96, 6
	v_sub_u32_e32 v0, v0, v34
	s_add_i32 s97, s0, 0x7f
	v_subrev_u32_e32 v240, s0, v0
	s_and_b32 s0, s74, 63
	s_lshl_b32 s0, s0, 7
	v_mov_b32_e32 v0, 0
	v_mul_f32_e32 v237, 0x42000000, v208
	v_add_u32_e32 v238, 0, v36
	v_xor_b32_e32 v239, 64, v235
	s_add_i32 s73, s33, -2
	s_add_i32 s79, s77, 0x18000
	s_sub_i32 s74, 0, s0
	v_mov_b32_e32 v1, v0
	v_mov_b32_e32 v2, v0
	v_mov_b32_e32 v3, v0
	v_mov_b32_e32 v4, v0
	v_mov_b32_e32 v5, v0
	v_mov_b32_e32 v6, v0
	v_mov_b32_e32 v7, v0
	v_mov_b32_e32 v8, v0
	v_mov_b32_e32 v9, v0
	v_mov_b32_e32 v10, v0
	v_mov_b32_e32 v11, v0
	v_mov_b32_e32 v12, v0
	v_mov_b32_e32 v13, v0
	v_mov_b32_e32 v14, v0
	v_mov_b32_e32 v15, v0
	v_mov_b32_e32 v16, v0
	v_mov_b32_e32 v17, v0
	v_mov_b32_e32 v18, v0
	v_mov_b32_e32 v19, v0
	v_mov_b32_e32 v20, v0
	v_mov_b32_e32 v21, v0
	v_mov_b32_e32 v22, v0
	v_mov_b32_e32 v23, v0
	v_mov_b32_e32 v24, v0
	v_mov_b32_e32 v25, v0
	v_mov_b32_e32 v26, v0
	v_mov_b32_e32 v27, v0
	v_mov_b32_e32 v28, v0
	v_mov_b32_e32 v29, v0
	v_mov_b32_e32 v30, v0
	v_mov_b32_e32 v31, v0
	v_mov_b32_e32 v32, v0
	v_mov_b32_e32 v33, v0
	v_mov_b32_e32 v34, v0
	v_mov_b32_e32 v35, v0
	v_mov_b32_e32 v36, v0
	v_mov_b32_e32 v37, v0
	v_mov_b32_e32 v38, v0
	v_mov_b32_e32 v39, v0
	v_mov_b32_e32 v40, v0
	v_mov_b32_e32 v41, v0
	v_mov_b32_e32 v42, v0
	v_mov_b32_e32 v43, v0
	v_mov_b32_e32 v44, v0
	v_mov_b32_e32 v45, v0
	v_mov_b32_e32 v46, v0
	v_mov_b32_e32 v47, v0
	v_mov_b32_e32 v48, v0
	v_mov_b32_e32 v49, v0
	v_mov_b32_e32 v50, v0
	v_mov_b32_e32 v51, v0
	v_mov_b32_e32 v52, v0
	v_mov_b32_e32 v53, v0
	v_mov_b32_e32 v54, v0
	v_mov_b32_e32 v55, v0
	v_mov_b32_e32 v56, v0
	v_mov_b32_e32 v57, v0
	v_mov_b32_e32 v58, v0
	v_mov_b32_e32 v59, v0
	v_mov_b32_e32 v60, v0
	v_mov_b32_e32 v61, v0
	v_mov_b32_e32 v62, v0
	v_mov_b32_e32 v63, v0
	v_add_u32_e32 v222, v238, v230
	v_add_u32_e32 v223, v238, v231
	v_add_u32_e32 v241, v238, v232
	v_add_u32_e32 v242, v238, v233
	s_sub_i32 s101, s78, s97
	s_ashr_i32 s101, s101, 6
	s_add_i32 s98, s33, -3
	s_add_i32 s99, s82, -1
	s_add_i32 s100, s74, s97
	s_sub_i32 s100, s100, 63
	v_mov_b32_e32 v166, v160
	v_mov_b32_e32 v167, v161
	v_mov_b32_e32 v168, v162
	v_mov_b32_e32 v169, v163
	v_mov_b32_e32 v162, v156
	v_mov_b32_e32 v163, v157
	v_mov_b32_e32 v164, v158
	v_mov_b32_e32 v165, v159
	v_mov_b32_e32 v174, v152
	v_mov_b32_e32 v175, v153
	v_mov_b32_e32 v176, v154
	v_mov_b32_e32 v177, v155
	v_mov_b32_e32 v170, v148
	v_mov_b32_e32 v171, v149
	v_mov_b32_e32 v172, v150
	v_mov_b32_e32 v173, v151
	s_cmp_ge_i32 s72, s73
	s_mov_b64 s[0:1], -1
	s_cbranch_scc0 .LBB0_321

.Lk_top:
	ds_read_b128 v[182:185], v85 offset:16384
	ds_read_b128 v[178:181], v254 offset:16384
	ds_read_b128 v[148:151], v255 offset:16384
	ds_read_b128 v[152:155], v84 offset:16384
	ds_read_b128 v[186:189], v85 offset:20480
	ds_read_b128 v[190:193], v254 offset:20480
	ds_read_b128 v[246:249], v255 offset:20480
	ds_read_b128 v[250:253], v84 offset:20480
	s_cmp_ge_i32 s72, s98
	s_cbranch_scc1 .LBB0_325
	s_add_i32 m0, s1, s94
	s_add_i32 s4, s90, s1
	global_load_lds_dwordx4 v[220:221], off
	s_mov_b32 m0, s4
	s_add_i32 s4, s1, s66
	global_load_lds_dwordx4 v[218:219], off
	s_mov_b32 m0, s4
	global_load_lds_dwordx4 v[224:225], off
	global_load_lds_dwordx4 v[224:225], off offset:1024
.LBB0_325:
	s_waitcnt lgkmcnt(4)
	v_mfma_f32_32x32x16_bf16 v[96:111], v[182:185], v[144:147], v[64:79]
	v_add_f32_e32 v229, v229, v198
	v_add_f32_e32 v229, v229, v199
	v_cvt_pk_bf16_f32 v166, v198, v199
	v_mfma_f32_32x32x16_bf16 v[96:111], v[178:181], v[140:143], v[96:111]
	v_cvt_f32_i32_e32 v156, s100
	v_add_f32_e32 v229, v229, v200
	v_add_f32_e32 v229, v229, v201
	v_cvt_pk_bf16_f32 v167, v200, v201
	v_mfma_f32_32x32x16_bf16 v[96:111], v[148:151], v[136:139], v[96:111]
	v_fma_f32 v254, v208, v156, -v207
	v_add_f32_e32 v229, v229, v202
	v_add_f32_e32 v229, v229, v203
	v_cvt_pk_bf16_f32 v168, v202, v203
	v_mfma_f32_32x32x16_bf16 v[96:111], v[152:155], v[132:135], v[96:111]
	v_add_f32_e32 v255, v237, v254
	v_add_f32_e32 v229, v229, v204
	v_add_f32_e32 v229, v229, v205
	v_cvt_pk_bf16_f32 v169, v204, v205
	s_add_i32 s3, s79, 0xfffe8000
	s_and_b32 s3, s3, 0x18000
	v_add_u32_e32 v158, s3, v235
	v_add_u32_e32 v159, s3, v239
	v_add_u32_e32 v160, s3, v236
	v_add_u32_e32 v161, s3, v234
	ds_read_b64_tr_b16 v[182:183], v158 offset:32768
	ds_read_b64_tr_b16 v[184:185], v158 offset:34816
	ds_read_b64_tr_b16 v[178:179], v159 offset:32768
	ds_read_b64_tr_b16 v[180:181], v159 offset:34816
	ds_read_b64_tr_b16 v[148:149], v160 offset:32768
	ds_read_b64_tr_b16 v[150:151], v160 offset:34816
	ds_read_b64_tr_b16 v[152:153], v161 offset:32768
	ds_read_b64_tr_b16 v[154:155], v161 offset:34816
	s_waitcnt lgkmcnt(8)
	v_mfma_f32_32x32x16_bf16 v[80:95], v[186:189], v[144:147], v[64:79]
	v_add_f32_e32 v96, v254, v96
	v_exp_f32_e32 v96, v96
	v_add_f32_e32 v97, v254, v97
	v_exp_f32_e32 v97, v97
	v_add_f32_e32 v98, v254, v98
	v_exp_f32_e32 v98, v98
	v_add_f32_e32 v99, v254, v99
	v_exp_f32_e32 v99, v99
	v_mfma_f32_32x32x16_bf16 v[80:95], v[190:193], v[140:143], v[80:95]
	v_add_f32_e32 v100, v254, v100
	v_exp_f32_e32 v100, v100
	v_add_f32_e32 v101, v254, v101
	v_exp_f32_e32 v101, v101
	v_add_f32_e32 v102, v254, v102
	v_exp_f32_e32 v102, v102
	v_add_f32_e32 v103, v254, v103
	v_exp_f32_e32 v103, v103
	v_mfma_f32_32x32x16_bf16 v[80:95], v[246:249], v[136:139], v[80:95]
	v_add_f32_e32 v104, v254, v104
	v_exp_f32_e32 v104, v104
	v_add_f32_e32 v105, v254, v105
	v_exp_f32_e32 v105, v105
	v_add_f32_e32 v106, v254, v106
	v_exp_f32_e32 v106, v106
	v_add_f32_e32 v107, v254, v107
	v_exp_f32_e32 v107, v107
	v_mfma_f32_32x32x16_bf16 v[80:95], v[250:253], v[132:135], v[80:95]
	v_add_f32_e32 v108, v254, v108
	v_exp_f32_e32 v108, v108
	v_add_f32_e32 v109, v254, v109
	v_exp_f32_e32 v109, v109
	v_add_f32_e32 v110, v254, v110
	v_exp_f32_e32 v110, v110
	v_add_f32_e32 v111, v254, v111
	v_exp_f32_e32 v111, v111
	s_cmp_le_i32 s72, s101
	s_cbranch_scc0 .Lmask_blk
.LBB0_327:
	s_waitcnt lgkmcnt(4)
	v_mfma_f32_32x32x16_bf16 v[48:63], v[182:185], v[174:177], v[48:63]
	v_add_f32_e32 v190, v255, v80
	v_exp_f32_e32 v190, v190
	ds_read_b64_tr_b16 v[246:247], v158 offset:36864
	ds_read_b64_tr_b16 v[248:249], v158 offset:38912
	v_add_f32_e32 v157, v190, v96
	v_mfma_f32_32x32x16_bf16 v[32:47], v[178:181], v[174:177], v[32:47]
	v_add_f32_e32 v191, v255, v81
	v_exp_f32_e32 v191, v191
	ds_read_b64_tr_b16 v[250:251], v159 offset:36864
	ds_read_b64_tr_b16 v[252:253], v159 offset:38912
	v_add_f32_e32 v156, v191, v97
	v_add_f32_e32 v157, v156, v157
	s_waitcnt lgkmcnt(4)
	v_mfma_f32_32x32x16_bf16 v[16:31], v[148:151], v[174:177], v[16:31]
	v_add_f32_e32 v192, v255, v82
	v_exp_f32_e32 v192, v192
	ds_read_b64_tr_b16 v[182:183], v160 offset:36864
	ds_read_b64_tr_b16 v[184:185], v160 offset:38912
	v_add_f32_e32 v156, v192, v98
	v_add_f32_e32 v157, v156, v157
	v_mfma_f32_32x32x16_bf16 v[0:15], v[152:155], v[174:177], v[0:15]
	v_add_f32_e32 v193, v255, v83
	v_exp_f32_e32 v193, v193
	ds_read_b64_tr_b16 v[178:179], v161 offset:36864
	ds_read_b64_tr_b16 v[180:181], v161 offset:38912
	v_add_f32_e32 v156, v193, v99
	v_add_f32_e32 v157, v156, v157
	v_cvt_pk_bf16_f32 v174, v96, v97
	s_waitcnt lgkmcnt(4)
	v_mfma_f32_32x32x16_bf16 v[48:63], v[246:249], v[162:165], v[48:63]
	v_add_f32_e32 v194, v255, v84
	v_exp_f32_e32 v194, v194
	ds_read_b64_tr_b16 v[148:149], v158 offset:40960
	ds_read_b64_tr_b16 v[150:151], v158 offset:43008
	v_add_f32_e32 v156, v194, v100
	v_add_f32_e32 v157, v156, v157
	v_cvt_pk_bf16_f32 v175, v98, v99
	v_mfma_f32_32x32x16_bf16 v[32:47], v[250:253], v[162:165], v[32:47]
	v_add_f32_e32 v195, v255, v85
	v_exp_f32_e32 v195, v195
	ds_read_b64_tr_b16 v[152:153], v159 offset:40960
	ds_read_b64_tr_b16 v[154:155], v159 offset:43008
	v_add_f32_e32 v156, v195, v101
	v_add_f32_e32 v157, v156, v157
	v_cvt_pk_bf16_f32 v176, v100, v101
	s_waitcnt lgkmcnt(4)
	v_mfma_f32_32x32x16_bf16 v[16:31], v[182:185], v[162:165], v[16:31]
	v_add_f32_e32 v196, v255, v86
	v_exp_f32_e32 v196, v196
	ds_read_b64_tr_b16 v[246:247], v160 offset:40960
	ds_read_b64_tr_b16 v[248:249], v160 offset:43008
	v_add_f32_e32 v156, v196, v102
	v_add_f32_e32 v157, v156, v157
	v_cvt_pk_bf16_f32 v177, v102, v103
	v_mfma_f32_32x32x16_bf16 v[0:15], v[178:181], v[162:165], v[0:15]
	v_add_f32_e32 v197, v255, v87
	v_exp_f32_e32 v197, v197
	ds_read_b64_tr_b16 v[250:251], v161 offset:40960
	ds_read_b64_tr_b16 v[252:253], v161 offset:43008
	v_add_f32_e32 v156, v197, v103
	v_add_f32_e32 v157, v156, v157
	v_cvt_pk_bf16_f32 v162, v104, v105
	s_waitcnt lgkmcnt(4)
	v_mfma_f32_32x32x16_bf16 v[48:63], v[148:151], v[170:173], v[48:63]
	v_add_f32_e32 v198, v255, v88
	v_exp_f32_e32 v198, v198
	ds_read_b64_tr_b16 v[182:183], v158 offset:45056
	ds_read_b64_tr_b16 v[184:185], v158 offset:47104
	v_add_f32_e32 v157, v104, v157
	v_cvt_pk_bf16_f32 v163, v106, v107
	v_mfma_f32_32x32x16_bf16 v[32:47], v[152:155], v[170:173], v[32:47]
	v_add_f32_e32 v199, v255, v89
	v_exp_f32_e32 v199, v199
	ds_read_b64_tr_b16 v[178:179], v159 offset:45056
	ds_read_b64_tr_b16 v[180:181], v159 offset:47104
	v_add_f32_e32 v157, v105, v157
	v_cvt_pk_bf16_f32 v164, v108, v109
	s_waitcnt lgkmcnt(4)
	v_mfma_f32_32x32x16_bf16 v[16:31], v[246:249], v[170:173], v[16:31]
	v_add_f32_e32 v200, v255, v90
	v_exp_f32_e32 v200, v200
	ds_read_b64_tr_b16 v[148:149], v160 offset:45056
	ds_read_b64_tr_b16 v[150:151], v160 offset:47104
	v_add_f32_e32 v157, v106, v157
	v_cvt_pk_bf16_f32 v165, v110, v111
	v_mfma_f32_32x32x16_bf16 v[0:15], v[250:253], v[170:173], v[0:15]
	v_add_f32_e32 v201, v255, v91
	v_exp_f32_e32 v201, v201
	ds_read_b64_tr_b16 v[152:153], v161 offset:45056
	ds_read_b64_tr_b16 v[154:155], v161 offset:47104
	v_add_f32_e32 v157, v107, v157
	v_cvt_pk_bf16_f32 v170, v190, v191
	s_waitcnt lgkmcnt(4)
	v_mfma_f32_32x32x16_bf16 v[48:63], v[182:185], v[166:169], v[48:63]
	v_add_f32_e32 v202, v255, v92
	v_exp_f32_e32 v202, v202
	v_cvt_pk_bf16_f32 v171, v192, v193
	v_add_f32_e32 v157, v108, v157
	v_mfma_f32_32x32x16_bf16 v[32:47], v[178:181], v[166:169], v[32:47]
	v_add_f32_e32 v203, v255, v93
	v_exp_f32_e32 v203, v203
	v_cvt_pk_bf16_f32 v172, v194, v195
	v_add_f32_e32 v157, v109, v157
	s_waitcnt lgkmcnt(0)
	v_mfma_f32_32x32x16_bf16 v[16:31], v[148:151], v[166:169], v[16:31]
	v_add_f32_e32 v204, v255, v94
	v_exp_f32_e32 v204, v204
	v_cvt_pk_bf16_f32 v173, v196, v197
	v_add_f32_e32 v157, v110, v157
	v_mfma_f32_32x32x16_bf16 v[0:15], v[152:155], v[166:169], v[0:15]
	v_add_f32_e32 v205, v255, v95
	v_exp_f32_e32 v205, v205
	v_add_f32_e32 v157, v111, v157
	s_add_i32 s72, s72, 1
	s_add_i32 s79, s79, 0x8000
	s_add_i32 s100, s100, 64
	v_add_f32_e32 v229, v229, v157
	v_lshl_add_u64 v[218:219], v[218:219], 0, s[88:89]
	v_lshl_add_u64 v[220:221], v[220:221], 0, s[88:89]
	v_lshl_add_u64 v[224:225], v[224:225], 0, s[92:93]
	s_and_b32 s1, s79, 0x18000
	s_xor_b32 s0, s1, 0x10000
	v_add_u32_e32 v85, s0, v222
	v_add_u32_e32 v254, s0, v223
	v_add_u32_e32 v255, s0, v241
	v_add_u32_e32 v84, s0, v242
	s_cmp_ge_i32 s72, s99
	s_cbranch_scc1 .LBB0_332
	s_cmp_ge_i32 s72, s73
	s_cbranch_scc1 .Lk_last
	s_waitcnt vmcnt(4) lgkmcnt(0)
	s_barrier
	s_branch .Lk_top

.LBB0_332:
	v_add_f32_e32 v229, v229, v198
	v_add_f32_e32 v229, v229, v199
	v_add_f32_e32 v229, v229, v200
	v_add_f32_e32 v229, v229, v201
	v_add_f32_e32 v229, v229, v202
	v_add_f32_e32 v229, v229, v203
	v_add_f32_e32 v229, v229, v204
	v_add_f32_e32 v229, v229, v205
	v_cvt_pk_bf16_f32 v166, v198, v199
	v_cvt_pk_bf16_f32 v167, v200, v201
	v_cvt_pk_bf16_f32 v168, v202, v203
	v_cvt_pk_bf16_f32 v169, v204, v205
	v_mov_b32_e32 v152, v174
	v_mov_b32_e32 v153, v175
	v_mov_b32_e32 v154, v176
	v_mov_b32_e32 v155, v177
	v_mov_b32_e32 v156, v162
	v_mov_b32_e32 v157, v163
	v_mov_b32_e32 v158, v164
	v_mov_b32_e32 v159, v165
	v_mov_b32_e32 v148, v170
	v_mov_b32_e32 v149, v171
	v_mov_b32_e32 v150, v172
	v_mov_b32_e32 v151, v173
	v_mov_b32_e32 v160, v166
	v_mov_b32_e32 v161, v167
	v_mov_b32_e32 v162, v168
	v_mov_b32_e32 v163, v169
	v_readlane_b32 s79, v244, 28
